# attention QK^T: K fragments of the next head-dim step requested before the current step's MFMAs (second fragment buffer)
# baseline (speedup 1.0000x reference)
.LBB0_339:
	ds_read_b128 v[64:67], v191 offset:49152
	ds_read_b128 v[68:71], v191 offset:57344
	ds_read_b128 v[208:211], v203 offset:49152
	ds_read_b128 v[212:215], v203 offset:57344
	ds_read_b128 v[216:219], v202 offset:49152
	ds_read_b128 v[220:223], v202 offset:57344
	v_add_f32_e32 v160, 0, v161
	v_add_f32_e32 v160, v175, v160
	s_waitcnt lgkmcnt(5)
	v_mfma_f32_32x32x16_bf16 v[80:95], v[64:67], v[112:115], 0
	v_add_f32_e32 v160, v162, v160
	v_add_f32_e32 v160, v184, v160
	v_add_f32_e32 v160, v174, v160
	v_add_f32_e32 v160, v185, v160
	v_add_f32_e32 v160, v163, v160
	v_add_f32_e32 v160, v173, v160
	v_add_f32_e32 v160, v169, v160
	s_waitcnt lgkmcnt(4)
	v_mfma_f32_32x32x16_bf16 v[64:79], v[68:71], v[112:115], 0
	v_add_f32_e32 v160, v171, v160
	v_add_f32_e32 v160, v170, v160
	v_add_f32_e32 v160, v172, v160
	v_exp_f32_e32 v158, v158
	v_add_f32_e32 v160, v165, v160
	v_exp_f32_e32 v159, v159
	v_add_f32_e32 v160, v167, v160
	s_waitcnt lgkmcnt(3)
	v_mfma_f32_32x32x16_bf16 v[80:95], v[208:211], v[104:107], v[80:95]
	v_exp_f32_e32 v156, v156
	v_add_f32_e32 v160, v166, v160
	v_exp_f32_e32 v157, v157
	v_add_f32_e32 v160, v168, v160
	v_exp_f32_e32 v152, v152
	v_add_f32_e32 v160, v158, v160
	v_exp_f32_e32 v153, v153
	s_waitcnt lgkmcnt(2)
	v_mfma_f32_32x32x16_bf16 v[64:79], v[212:215], v[104:107], v[64:79]
	ds_read_b128 v[208:211], v200 offset:49152
	ds_read_b128 v[212:215], v200 offset:57344
	v_add_f32_e32 v160, v159, v160
	v_exp_f32_e32 v148, v148
	v_add_f32_e32 v160, v156, v160
	v_exp_f32_e32 v149, v149
	v_add_f32_e32 v160, v157, v160
	v_exp_f32_e32 v146, v146
	s_waitcnt lgkmcnt(3)
	v_mfma_f32_32x32x16_bf16 v[80:95], v[216:219], v[120:123], v[80:95]
	v_add_f32_e32 v160, v152, v160
	v_exp_f32_e32 v147, v147
	v_add_f32_e32 v160, v153, v160
	v_exp_f32_e32 v154, v154
	v_add_f32_e32 v160, v148, v160
	v_exp_f32_e32 v155, v155
	v_add_f32_e32 v160, v149, v160
	s_waitcnt lgkmcnt(2)
	v_mfma_f32_32x32x16_bf16 v[64:79], v[220:223], v[120:123], v[64:79]
	ds_read_b128 v[216:219], v199 offset:49152
	ds_read_b128 v[220:223], v199 offset:57344
	v_exp_f32_e32 v150, v150
	v_add_f32_e32 v160, v146, v160
	v_exp_f32_e32 v151, v151
	v_add_f32_e32 v160, v147, v160
	v_exp_f32_e32 v144, v144
	v_add_f32_e32 v160, v154, v160
	s_waitcnt lgkmcnt(3)
	v_mfma_f32_32x32x16_bf16 v[80:95], v[208:211], v[124:127], v[80:95]
	v_exp_f32_e32 v145, v145
	v_add_f32_e32 v160, v155, v160
	v_add_f32_e32 v160, v150, v160
	v_add_f32_e32 v160, v151, v160
	v_add_f32_e32 v160, v144, v160
	v_add_f32_e32 v207, v145, v160
	s_waitcnt lgkmcnt(2)
	v_mfma_f32_32x32x16_bf16 v[64:79], v[212:215], v[124:127], v[64:79]
	ds_read_b128 v[208:211], v201 offset:49152
	ds_read_b128 v[212:215], v201 offset:57344
	s_waitcnt lgkmcnt(3)
	v_mfma_f32_32x32x16_bf16 v[80:95], v[216:219], v[116:119], v[80:95]
	s_waitcnt lgkmcnt(2)
	v_mfma_f32_32x32x16_bf16 v[64:79], v[220:223], v[116:119], v[64:79]
	ds_read_b128 v[216:219], v205 offset:49152
	ds_read_b128 v[220:223], v205 offset:57344
	s_waitcnt lgkmcnt(3)
	v_mfma_f32_32x32x16_bf16 v[80:95], v[208:211], v[108:111], v[80:95]
	s_waitcnt lgkmcnt(2)
	v_mfma_f32_32x32x16_bf16 v[64:79], v[212:215], v[108:111], v[64:79]
	ds_read_b128 v[208:211], v204 offset:49152
	ds_read_b128 v[212:215], v204 offset:57344
	s_waitcnt lgkmcnt(3)
	v_mfma_f32_32x32x16_bf16 v[80:95], v[216:219], v[100:103], v[80:95]
	s_waitcnt lgkmcnt(2)
	v_mfma_f32_32x32x16_bf16 v[64:79], v[220:223], v[100:103], v[64:79]
	v_cvt_pk_bf16_f32 v160, v161, v175
	v_cvt_pk_bf16_f32 v161, v162, v184
	v_cvt_pk_bf16_f32 v162, v174, v185
	v_cvt_pk_bf16_f32 v163, v163, v173
	s_nop 0
	v_permlane32_swap_b32_e32 v160, v162
	s_waitcnt lgkmcnt(1)
	v_mfma_f32_32x32x16_bf16 v[80:95], v[208:211], v[96:99], v[80:95]
	v_mov_b32_e32 v208, v207
	s_nop 1
	v_permlane32_swap_b32_e32 v207, v208
	v_cvt_pk_bf16_f32 v210, v169, v171
	v_cvt_pk_bf16_f32 v211, v170, v172
	v_permlane32_swap_b32_e32 v161, v163
	s_waitcnt lgkmcnt(0)
	v_mfma_f32_32x32x16_bf16 v[64:79], v[212:215], v[96:99], v[64:79]
	v_cvt_pk_bf16_f32 v212, v165, v167
	v_cvt_pk_bf16_f32 v213, v166, v168
	v_cvt_pk_bf16_f32 v166, v158, v159
	v_cvt_pk_bf16_f32 v167, v156, v157
	v_cvt_pk_bf16_f32 v168, v152, v153
	v_cvt_pk_bf16_f32 v169, v148, v149
	v_cvt_pk_bf16_f32 v170, v146, v147
	v_cvt_pk_bf16_f32 v171, v154, v155
	v_cvt_pk_bf16_f32 v172, v150, v151
	v_cvt_pk_bf16_f32 v173, v144, v145
	s_nop 0
	v_permlane32_swap_b32_e32 v210, v212
	v_permlane32_swap_b32_e32 v211, v213
	v_permlane32_swap_b32_e32 v166, v168
	v_permlane32_swap_b32_e32 v167, v169
	v_permlane32_swap_b32_e32 v170, v172
	v_permlane32_swap_b32_e32 v171, v173
	v_lshl_add_u64 v[186:187], s[20:21], 0, v[192:193]
	v_add_co_u32_e32 v148, vcc, s41, v186
	v_lshl_add_u64 v[184:185], s[20:21], 0, v[182:183]
	s_nop 0
	v_addc_co_u32_e32 v149, vcc, 0, v187, vcc
	v_add_co_u32_e32 v152, vcc, s41, v184
	s_nop 1
	v_addc_co_u32_e32 v153, vcc, 0, v185, vcc
	global_load_dwordx4 v[144:147], v[148:149], off offset:3584
	s_nop 0
	global_load_dwordx4 v[148:151], v[148:149], off offset:3072
	s_nop 0
	global_load_dwordx4 v[156:159], v[152:153], off offset:3584
	s_nop 0
	global_load_dwordx4 v[152:155], v[152:153], off offset:3072
	ds_read_b64_tr_b16 v[214:215], v190 offset:0
	ds_read_b64_tr_b16 v[216:217], v190 offset:0x800
	ds_read_b64_tr_b16 v[218:219], v190 offset:0x1000
	ds_read_b64_tr_b16 v[220:221], v190 offset:0x1800
	ds_read_b64_tr_b16 v[246:247], v190 offset:0x2000
	ds_read_b64_tr_b16 v[248:249], v190 offset:0x2800
	ds_read_b64_tr_b16 v[232:233], v190 offset:0x3000
	ds_read_b64_tr_b16 v[234:235], v190 offset:0x3800
	s_waitcnt lgkmcnt(0)
	s_nop 0
	v_mfma_f32_32x32x16_bf16 v[0:15], v[160:163], v[214:217], v[0:15]
	ds_read_b64_tr_b16 v[214:215], v190 offset:0x200
	ds_read_b64_tr_b16 v[216:217], v190 offset:0xa00
	v_mfma_f32_32x32x16_bf16 v[0:15], v[210:213], v[218:221], v[0:15]
	ds_read_b64_tr_b16 v[218:219], v190 offset:0x1200
	ds_read_b64_tr_b16 v[220:221], v190 offset:0x1a00
	v_mfma_f32_32x32x16_bf16 v[0:15], v[166:169], v[246:249], v[0:15]
	v_mfma_f32_32x32x16_bf16 v[0:15], v[170:173], v[232:235], v[0:15]
	ds_read_b64_tr_b16 v[232:233], v190 offset:0x2200
	ds_read_b64_tr_b16 v[234:235], v190 offset:0x2a00
	ds_read_b64_tr_b16 v[246:247], v190 offset:0x3200
	ds_read_b64_tr_b16 v[248:249], v190 offset:0x3a00
	s_waitcnt lgkmcnt(0)
	v_mfma_f32_32x32x16_bf16 v[48:63], v[160:163], v[214:217], v[48:63]
	ds_read_b64_tr_b16 v[214:215], v190 offset:0x400
	ds_read_b64_tr_b16 v[216:217], v190 offset:0xc00
	v_mfma_f32_32x32x16_bf16 v[48:63], v[210:213], v[218:221], v[48:63]
	ds_read_b64_tr_b16 v[218:219], v190 offset:0x1400
	ds_read_b64_tr_b16 v[220:221], v190 offset:0x1c00
	v_mfma_f32_32x32x16_bf16 v[48:63], v[166:169], v[232:235], v[48:63]
	ds_read_b64_tr_b16 v[232:233], v190 offset:0x2400
	ds_read_b64_tr_b16 v[234:235], v190 offset:0x2c00
	v_mfma_f32_32x32x16_bf16 v[48:63], v[170:173], v[246:249], v[48:63]
	ds_read_b64_tr_b16 v[246:247], v190 offset:0x3400
	ds_read_b64_tr_b16 v[248:249], v190 offset:0x3c00
	s_waitcnt lgkmcnt(0)
	v_mfma_f32_32x32x16_bf16 v[32:47], v[160:163], v[214:217], v[32:47]
	ds_read_b64_tr_b16 v[214:215], v190 offset:0x600
	ds_read_b64_tr_b16 v[216:217], v190 offset:0xe00
	v_mfma_f32_32x32x16_bf16 v[32:47], v[210:213], v[218:221], v[32:47]
	ds_read_b64_tr_b16 v[218:219], v190 offset:0x1600
	ds_read_b64_tr_b16 v[220:221], v190 offset:0x1e00
	v_mfma_f32_32x32x16_bf16 v[32:47], v[166:169], v[232:235], v[32:47]
	ds_read_b64_tr_b16 v[232:233], v190 offset:0x2600
	ds_read_b64_tr_b16 v[234:235], v190 offset:0x2e00
	v_mfma_f32_32x32x16_bf16 v[32:47], v[170:173], v[246:249], v[32:47]
	ds_read_b64_tr_b16 v[246:247], v190 offset:0x3600
	ds_read_b64_tr_b16 v[248:249], v190 offset:0x3e00
	s_waitcnt lgkmcnt(0)
	v_mfma_f32_32x32x16_bf16 v[16:31], v[160:163], v[214:217], v[16:31]
	v_max_f32_e32 v160, v81, v81
	v_max_f32_e32 v161, v80, v80
	v_max_f32_e32 v160, v161, v160
	v_max3_f32 v160, v160, v82, v83
	v_max3_f32 v160, v160, v84, v85
	v_max3_f32 v160, v160, v86, v87
	v_max3_f32 v160, v160, v88, v89
	v_max3_f32 v160, v160, v90, v91
	v_max3_f32 v160, v160, v92, v93
	v_mfma_f32_32x32x16_bf16 v[16:31], v[210:213], v[218:221], v[16:31]
	v_max3_f32 v160, v160, v94, v95
	v_max3_f32 v160, v160, v64, v65
	v_max3_f32 v160, v160, v66, v67
	v_max3_f32 v160, v160, v68, v69
	v_max3_f32 v160, v160, v70, v71
	v_max3_f32 v160, v160, v72, v73
	v_max3_f32 v160, v160, v74, v75
	v_max3_f32 v160, v160, v76, v77
	v_mfma_f32_32x32x16_bf16 v[16:31], v[166:169], v[232:235], v[16:31]
	v_max3_f32 v160, v160, v78, v79
	v_mov_b32_e32 v161, v160
	s_nop 1
	v_permlane32_swap_b32_e32 v160, v161
	v_max_f32_e32 v161, v161, v161
	v_max_f32_e32 v160, v160, v160
	v_max_f32_e32 v160, v160, v161
	v_sub_f32_e32 v161, v160, v164
	v_cmp_ge_f32_e32 vcc, s40, v161
	v_max_f32_e32 v161, v164, v164
	v_max_f32_e32 v160, v161, v160
	v_mfma_f32_32x32x16_bf16 v[16:31], v[170:173], v[246:249], v[16:31]
	v_sub_f32_e32 v161, v164, v160
	v_mul_f32_e32 v161, 0x3e0293ee, v161
	v_exp_f32_e32 v161, v161
	s_cmp_eq_u64 vcc, exec
	s_cselect_b64 s[6:7], -1, 0
	s_barrier
	s_waitcnt vmcnt(4)
	v_cndmask_b32_e64 v209, v161, 1.0, s[6:7]
	v_cmp_gt_f32_e32 vcc, 1.0, v209
	s_waitcnt vmcnt(4)
	ds_write_b128 v197, v[128:131]
	ds_write_b128 v198, v[136:139]
	ds_write_b128 v195, v[140:143] offset:32768
	ds_write_b128 v196, v[132:135] offset:32768
	s_cbranch_vccz .LBB0_343
	s_and_saveexec_b64 s[22:23], s[4:5]
	ds_write_b32 v181, v209 offset:128
	s_or_b64 exec, exec, s[22:23]
	s_waitcnt lgkmcnt(0)
	v_add_u32_e32 v161, v179, v180
	ds_read2_b32 v[162:163], v161 offset0:48 offset1:49
	ds_read2_b32 v[166:167], v161 offset0:50 offset1:51
	ds_read2_b32 v[168:169], v161 offset0:56 offset1:57
	ds_read2_b32 v[170:171], v161 offset0:58 offset1:59
	ds_read2_b32 v[172:173], v161 offset0:32 offset1:33
	ds_read2_b32 v[174:175], v161 offset0:34 offset1:35
	ds_read2_b32 v[210:211], v161 offset0:40 offset1:41
	ds_read2_b32 v[212:213], v161 offset0:42 offset1:43
	s_waitcnt lgkmcnt(4)
	v_pk_mul_f32 v[14:15], v[14:15], v[170:171]
	v_pk_mul_f32 v[12:13], v[12:13], v[168:169]
	v_pk_mul_f32 v[10:11], v[10:11], v[166:167]
	v_pk_mul_f32 v[8:9], v[8:9], v[162:163]
	s_waitcnt lgkmcnt(0)
	v_pk_mul_f32 v[6:7], v[6:7], v[212:213]
	v_pk_mul_f32 v[4:5], v[4:5], v[210:211]
	v_pk_mul_f32 v[2:3], v[2:3], v[174:175]
	v_pk_mul_f32 v[0:1], v[0:1], v[172:173]
	v_pk_mul_f32 v[62:63], v[62:63], v[170:171]
	v_pk_mul_f32 v[60:61], v[60:61], v[168:169]
	v_pk_mul_f32 v[58:59], v[58:59], v[166:167]
	v_pk_mul_f32 v[56:57], v[56:57], v[162:163]
	v_pk_mul_f32 v[54:55], v[54:55], v[212:213]
	v_pk_mul_f32 v[52:53], v[52:53], v[210:211]
	v_pk_mul_f32 v[50:51], v[50:51], v[174:175]
	v_pk_mul_f32 v[48:49], v[48:49], v[172:173]
	v_pk_mul_f32 v[46:47], v[46:47], v[170:171]
	v_pk_mul_f32 v[44:45], v[44:45], v[168:169]
	v_pk_mul_f32 v[42:43], v[42:43], v[166:167]
	v_pk_mul_f32 v[40:41], v[40:41], v[162:163]
	v_pk_mul_f32 v[38:39], v[38:39], v[212:213]
	v_pk_mul_f32 v[36:37], v[36:37], v[210:211]
	v_pk_mul_f32 v[34:35], v[34:35], v[174:175]
	v_pk_mul_f32 v[32:33], v[32:33], v[172:173]
	v_pk_mul_f32 v[30:31], v[30:31], v[170:171]
	v_pk_mul_f32 v[28:29], v[28:29], v[168:169]
	v_pk_mul_f32 v[26:27], v[26:27], v[166:167]
	v_pk_mul_f32 v[24:25], v[24:25], v[162:163]
	v_pk_mul_f32 v[22:23], v[22:23], v[212:213]
	v_pk_mul_f32 v[20:21], v[20:21], v[210:211]
	v_pk_mul_f32 v[18:19], v[18:19], v[174:175]
	v_pk_mul_f32 v[16:17], v[16:17], v[172:173]
.LBB0_343:
	v_cndmask_b32_e64 v210, v160, v164, s[6:7]
	v_mul_f32_e32 v211, 0xbe0293ee, v210
	v_fmamk_f32 v80, v80, 0x3e0293ee, v211
	v_fmamk_f32 v81, v81, 0x3e0293ee, v211
	v_fmamk_f32 v82, v82, 0x3e0293ee, v211
	v_fmamk_f32 v83, v83, 0x3e0293ee, v211
	v_fmamk_f32 v84, v84, 0x3e0293ee, v211
	v_fmamk_f32 v85, v85, 0x3e0293ee, v211
	v_fmamk_f32 v86, v86, 0x3e0293ee, v211
	v_fmamk_f32 v87, v87, 0x3e0293ee, v211
	v_fmamk_f32 v88, v88, 0x3e0293ee, v211
	v_fmamk_f32 v89, v89, 0x3e0293ee, v211
	v_fmamk_f32 v90, v90, 0x3e0293ee, v211
	v_fmamk_f32 v91, v91, 0x3e0293ee, v211
	v_fmamk_f32 v92, v92, 0x3e0293ee, v211
	v_fmamk_f32 v93, v93, 0x3e0293ee, v211
	v_fmamk_f32 v94, v94, 0x3e0293ee, v211
	v_fmamk_f32 v95, v95, 0x3e0293ee, v211
	v_exp_f32_e32 v160, v80
	v_exp_f32_e32 v175, v81
	v_exp_f32_e32 v161, v82
	v_exp_f32_e32 v174, v83
	v_exp_f32_e32 v162, v84
	v_exp_f32_e32 v173, v85
	v_exp_f32_e32 v163, v86
	v_exp_f32_e32 v172, v87
	v_exp_f32_e32 v164, v88
	v_exp_f32_e32 v171, v89
	v_exp_f32_e32 v165, v90
	v_exp_f32_e32 v170, v91
	v_exp_f32_e32 v166, v92
	v_exp_f32_e32 v169, v93
	v_exp_f32_e32 v167, v94
	v_exp_f32_e32 v168, v95
	v_fmamk_f32 v220, v64, 0x3e0293ee, v211
	v_fmamk_f32 v221, v65, 0x3e0293ee, v211
	v_fmamk_f32 v222, v66, 0x3e0293ee, v211
	v_fmamk_f32 v223, v67, 0x3e0293ee, v211
	v_fmamk_f32 v245, v68, 0x3e0293ee, v211
	v_fmamk_f32 v213, v69, 0x3e0293ee, v211
	v_fmamk_f32 v214, v70, 0x3e0293ee, v211
	v_fmamk_f32 v215, v71, 0x3e0293ee, v211
	v_fmamk_f32 v216, v72, 0x3e0293ee, v211
	v_fmamk_f32 v217, v73, 0x3e0293ee, v211
	v_fmamk_f32 v218, v74, 0x3e0293ee, v211
	v_fmamk_f32 v219, v75, 0x3e0293ee, v211
	v_fmamk_f32 v212, v76, 0x3e0293ee, v211
	v_fmamk_f32 v246, v77, 0x3e0293ee, v211
	v_fmamk_f32 v247, v78, 0x3e0293ee, v211
	v_fmac_f32_e32 v211, 0x3e0293ee, v79
	s_waitcnt lgkmcnt(0)
	s_barrier
	ds_read_b128 v[64:67], v191 offset:32768
	ds_read_b128 v[68:71], v191 offset:40960
	ds_read_b128 v[232:235], v203 offset:32768
	ds_read_b128 v[248:251], v203 offset:40960
	ds_read_b128 v[128:131], v202 offset:32768
	ds_read_b128 v[132:135], v202 offset:40960
	v_exp_f32_e32 v236, v211
	v_add_f32_e32 v211, 0, v160
	s_waitcnt lgkmcnt(5)
	v_mfma_f32_32x32x16_bf16 v[80:95], v[64:67], v[112:115], 0
	v_add_f32_e32 v211, v175, v211
	v_add_f32_e32 v211, v161, v211
	v_add_f32_e32 v211, v174, v211
	v_add_f32_e32 v211, v162, v211
	v_add_f32_e32 v211, v173, v211
	v_add_f32_e32 v211, v163, v211
	v_add_f32_e32 v211, v172, v211
	s_waitcnt lgkmcnt(4)
	v_mfma_f32_32x32x16_bf16 v[64:79], v[68:71], v[112:115], 0
	v_add_f32_e32 v211, v164, v211
	v_add_f32_e32 v211, v171, v211
	v_add_f32_e32 v211, v165, v211
	v_add_f32_e32 v211, v170, v211
	v_exp_f32_e32 v220, v220
	v_add_f32_e32 v211, v166, v211
	v_exp_f32_e32 v221, v221
	s_waitcnt lgkmcnt(3)
	v_mfma_f32_32x32x16_bf16 v[80:95], v[232:235], v[104:107], v[80:95]
	v_add_f32_e32 v211, v169, v211
	v_exp_f32_e32 v222, v222
	v_add_f32_e32 v211, v167, v211
	v_exp_f32_e32 v223, v223
	v_add_f32_e32 v211, v168, v211
	v_add_f32_e32 v211, v220, v211
	v_exp_f32_e32 v213, v213
	s_waitcnt lgkmcnt(2)
	v_mfma_f32_32x32x16_bf16 v[64:79], v[248:251], v[104:107], v[64:79]
	ds_read_b128 v[232:235], v200 offset:32768
	ds_read_b128 v[248:251], v200 offset:40960
	v_add_f32_e32 v211, v221, v211
	v_exp_f32_e32 v214, v214
	v_add_f32_e32 v211, v222, v211
	v_exp_f32_e32 v215, v215
	v_add_f32_e32 v211, v223, v211
	v_exp_f32_e32 v216, v216
	s_waitcnt lgkmcnt(3)
	v_mfma_f32_32x32x16_bf16 v[80:95], v[128:131], v[120:123], v[80:95]
	v_exp_f32_e32 v217, v217
	v_exp_f32_e32 v218, v218
	v_exp_f32_e32 v219, v219
	s_waitcnt lgkmcnt(2)
	v_mfma_f32_32x32x16_bf16 v[64:79], v[132:135], v[120:123], v[64:79]
	ds_read_b128 v[128:131], v199 offset:32768
	ds_read_b128 v[132:135], v199 offset:40960
	s_waitcnt lgkmcnt(3)
	v_mfma_f32_32x32x16_bf16 v[80:95], v[232:235], v[124:127], v[80:95]
	s_waitcnt lgkmcnt(2)
	v_mfma_f32_32x32x16_bf16 v[64:79], v[248:251], v[124:127], v[64:79]
	ds_read_b128 v[232:235], v201 offset:32768
	ds_read_b128 v[248:251], v201 offset:40960
	s_waitcnt lgkmcnt(3)
	v_mfma_f32_32x32x16_bf16 v[80:95], v[128:131], v[116:119], v[80:95]
	s_waitcnt lgkmcnt(2)
	v_mfma_f32_32x32x16_bf16 v[64:79], v[132:135], v[116:119], v[64:79]
	ds_read_b128 v[128:131], v205 offset:32768
	ds_read_b128 v[132:135], v205 offset:40960
	s_waitcnt lgkmcnt(3)
	v_mfma_f32_32x32x16_bf16 v[80:95], v[232:235], v[108:111], v[80:95]
	s_waitcnt lgkmcnt(2)
	v_mfma_f32_32x32x16_bf16 v[64:79], v[248:251], v[108:111], v[64:79]
	ds_read_b128 v[232:235], v204 offset:32768
	ds_read_b128 v[248:251], v204 offset:40960
	s_waitcnt lgkmcnt(3)
	v_mfma_f32_32x32x16_bf16 v[80:95], v[128:131], v[100:103], v[80:95]
	s_waitcnt lgkmcnt(2)
	v_mfma_f32_32x32x16_bf16 v[64:79], v[132:135], v[100:103], v[64:79]
	v_cvt_pk_bf16_f32 v160, v160, v175
	v_cvt_pk_bf16_f32 v161, v161, v174
	v_cvt_pk_bf16_f32 v162, v162, v173
	v_cvt_pk_bf16_f32 v163, v163, v172
	v_cvt_pk_bf16_f32 v164, v164, v171
	v_cvt_pk_bf16_f32 v165, v165, v170
	s_waitcnt lgkmcnt(1)
	v_mfma_f32_32x32x16_bf16 v[80:95], v[232:235], v[96:99], v[80:95]
	v_exp_f32_e32 v232, v245
	v_exp_f32_e32 v233, v212
	v_exp_f32_e32 v234, v246
	v_exp_f32_e32 v235, v247
	v_add_f32_e32 v211, v232, v211
	v_add_f32_e32 v211, v213, v211
	v_add_f32_e32 v211, v214, v211
	v_add_f32_e32 v211, v215, v211
	v_add_f32_e32 v211, v216, v211
	v_add_f32_e32 v211, v217, v211
	s_waitcnt lgkmcnt(0)
	v_mfma_f32_32x32x16_bf16 v[64:79], v[248:251], v[96:99], v[64:79]
	v_add_f32_e32 v211, v218, v211
	v_add_f32_e32 v211, v219, v211
	v_add_f32_e32 v211, v233, v211
	v_add_f32_e32 v211, v234, v211
	v_add_f32_e32 v211, v235, v211
	v_add_f32_e32 v211, v236, v211
	v_mov_b32_e32 v212, v211
	v_cvt_pk_bf16_f32 v166, v166, v169
	v_cvt_pk_bf16_f32 v167, v167, v168
	v_cvt_pk_bf16_f32 v168, v220, v221
	v_cvt_pk_bf16_f32 v169, v222, v223
	v_cvt_pk_bf16_f32 v170, v232, v213
	v_cvt_pk_bf16_f32 v171, v214, v215
	v_cvt_pk_bf16_f32 v172, v216, v217
	v_cvt_pk_bf16_f32 v173, v218, v219
	v_cvt_pk_bf16_f32 v174, v233, v234
	v_cvt_pk_bf16_f32 v175, v235, v236
	s_nop 1
	v_permlane32_swap_b32_e32 v211, v212
	v_permlane32_swap_b32_e32 v160, v162
	v_permlane32_swap_b32_e32 v161, v163
	v_permlane32_swap_b32_e32 v164, v166
	v_permlane32_swap_b32_e32 v165, v167
	v_permlane32_swap_b32_e32 v168, v170
	v_permlane32_swap_b32_e32 v169, v171
	v_permlane32_swap_b32_e32 v172, v174
	v_permlane32_swap_b32_e32 v173, v175
	s_add_i32 s35, s35, 2
	s_cmp_ge_u32 s35, s34
	s_cselect_b64 s[22:23], -1, 0
	s_and_b64 vcc, exec, s[22:23]
	s_cbranch_vccnz .LBB0_345
	v_add_co_u32_e32 v132, vcc, 0x1f760000, v186
	s_nop 1
	v_addc_co_u32_e32 v133, vcc, 0, v187, vcc
	v_add_co_u32_e32 v134, vcc, 0x1f760000, v184
	s_nop 1
	v_addc_co_u32_e32 v135, vcc, 0, v185, vcc
	global_load_dwordx4 v[128:131], v[132:133], off offset:3584
	global_load_dwordx4 v[140:143], v[132:133], off offset:3072
	global_load_dwordx4 v[136:139], v[134:135], off offset:3584
	s_nop 0
	global_load_dwordx4 v[132:135], v[134:135], off offset:3072
